# v51 + mid-group s_setprio 0/1 flip pairs deleted inside the 32-MFMA groups of the five GEMM K-loops
# baseline (speedup 1.0000x reference)
.LBB0_124:
	ds_read_b128 v[154:157], v168
	ds_read_b128 v[158:161], v168 offset:1024
	ds_read_b128 v[162:165], v168 offset:2048
	ds_read_b128 v[172:175], v168 offset:3072
	ds_read_b128 v[176:179], v169
	ds_read_b128 v[180:183], v169 offset:1024
	ds_read_b128 v[184:187], v169 offset:2048
	ds_read_b128 v[188:191], v169 offset:3072
	s_add_u32 s18, s16, 0xfff00080
	s_addc_u32 s19, s17, -1
	s_cmp_eq_u32 s56, 60
	s_cselect_b32 s23, s15, s19
	s_cselect_b32 s22, s21, s18
	s_cselect_b32 s19, s24, s51
	s_cselect_b32 s18, s25, s49
	s_add_i32 m0, s70, 0xc000
	ds_read_b128 v[192:195], v170
	ds_read_b128 v[196:199], v170 offset:1024
	ds_read_b128 v[200:203], v170 offset:2048
	ds_read_b128 v[204:207], v170 offset:3072
	ds_read_b128 v[208:211], v170 offset:4096
	ds_read_b128 v[212:215], v170 offset:5120
	ds_read_b128 v[216:219], v170 offset:6144
	ds_read_b128 v[220:223], v170 offset:7168
	global_load_lds_dwordx4 v146, s[16:17]
	s_add_i32 m0, s70, 0xe000
	s_nop 0
	global_load_lds_dwordx4 v148, s[16:17]
	s_waitcnt vmcnt(8)
	s_waitcnt lgkmcnt(0)
	s_barrier
	s_setprio 1
	s_waitcnt lgkmcnt(0)
	v_mfma_f32_16x16x32_bf16 v[124:127], v[154:157], v[192:195], v[124:127]
	v_mfma_f32_16x16x32_bf16 v[120:123], v[162:165], v[192:195], v[120:123]
	v_mfma_f32_16x16x32_bf16 v[108:111], v[154:157], v[200:203], v[108:111]
	v_mfma_f32_16x16x32_bf16 v[104:107], v[162:165], v[200:203], v[104:107]
	v_mfma_f32_16x16x32_bf16 v[92:95], v[154:157], v[208:211], v[92:95]
	v_mfma_f32_16x16x32_bf16 v[88:91], v[162:165], v[208:211], v[88:91]
	v_mfma_f32_16x16x32_bf16 v[76:79], v[154:157], v[216:219], v[76:79]
	v_mfma_f32_16x16x32_bf16 v[72:75], v[162:165], v[216:219], v[72:75]
	v_mfma_f32_16x16x32_bf16 v[124:127], v[158:161], v[196:199], v[124:127]
	v_mfma_f32_16x16x32_bf16 v[120:123], v[172:175], v[196:199], v[120:123]
	v_mfma_f32_16x16x32_bf16 v[108:111], v[158:161], v[204:207], v[108:111]
	v_mfma_f32_16x16x32_bf16 v[104:107], v[172:175], v[204:207], v[104:107]
	v_mfma_f32_16x16x32_bf16 v[92:95], v[158:161], v[212:215], v[92:95]
	v_mfma_f32_16x16x32_bf16 v[88:91], v[172:175], v[212:215], v[88:91]
	v_mfma_f32_16x16x32_bf16 v[76:79], v[158:161], v[220:223], v[76:79]
	v_mfma_f32_16x16x32_bf16 v[72:75], v[172:175], v[220:223], v[72:75]
	v_mfma_f32_16x16x32_bf16 v[116:119], v[176:179], v[192:195], v[116:119]
	v_mfma_f32_16x16x32_bf16 v[112:115], v[184:187], v[192:195], v[112:115]
	v_mfma_f32_16x16x32_bf16 v[100:103], v[176:179], v[200:203], v[100:103]
	v_mfma_f32_16x16x32_bf16 v[96:99], v[184:187], v[200:203], v[96:99]
	v_mfma_f32_16x16x32_bf16 v[84:87], v[176:179], v[208:211], v[84:87]
	v_mfma_f32_16x16x32_bf16 v[80:83], v[184:187], v[208:211], v[80:83]
	v_mfma_f32_16x16x32_bf16 v[68:71], v[176:179], v[216:219], v[68:71]
	v_mfma_f32_16x16x32_bf16 v[64:67], v[184:187], v[216:219], v[64:67]
	v_mfma_f32_16x16x32_bf16 v[116:119], v[180:183], v[196:199], v[116:119]
	v_mfma_f32_16x16x32_bf16 v[112:115], v[188:191], v[196:199], v[112:115]
	v_mfma_f32_16x16x32_bf16 v[100:103], v[180:183], v[204:207], v[100:103]
	v_mfma_f32_16x16x32_bf16 v[96:99], v[188:191], v[204:207], v[96:99]
	v_mfma_f32_16x16x32_bf16 v[84:87], v[180:183], v[212:215], v[84:87]
	v_mfma_f32_16x16x32_bf16 v[80:83], v[188:191], v[212:215], v[80:83]
	v_mfma_f32_16x16x32_bf16 v[68:71], v[180:183], v[220:223], v[68:71]
	v_mfma_f32_16x16x32_bf16 v[64:67], v[188:191], v[220:223], v[64:67]
	s_setprio 0
	s_barrier
	s_add_i32 s57, s77, s93
	s_mov_b32 m0, s57
	ds_read_b128 v[192:195], v170 offset:16384
	ds_read_b128 v[196:199], v170 offset:17408
	ds_read_b128 v[200:203], v170 offset:18432
	ds_read_b128 v[204:207], v170 offset:19456
	ds_read_b128 v[208:211], v170 offset:20480
	ds_read_b128 v[212:215], v170 offset:21504
	ds_read_b128 v[216:219], v170 offset:22528
	ds_read_b128 v[220:223], v170 offset:23552
	global_load_lds_dwordx4 v130, s[18:19]
	s_add_i32 m0, s57, 0x2000
	s_add_u32 s58, s18, 0x100000
	v_lshl_add_u64 v[224:225], s[18:19], 0, v[134:135]
	s_addc_u32 s59, s19, 0
	s_add_i32 s57, s78, s93
	global_load_lds_dwordx4 v134, s[18:19]
	s_mov_b32 m0, s57
	v_lshl_add_u64 v[228:229], s[22:23], 0, v[132:133]
	global_load_lds_dwordx4 v130, s[58:59]
	s_add_i32 m0, s57, 0x2000
	s_nop 0
	global_load_lds_dwordx4 v134, s[58:59]
	v_lshl_add_u64 v[226:227], s[22:23], 0, v[128:129]
	s_mov_b32 m0, s70
	s_nop 0
	global_load_lds_dwordx4 v128, s[22:23]
	s_mov_b32 m0, s71
	s_nop 0
	global_load_lds_dwordx4 v132, s[22:23]
	s_waitcnt vmcnt(8)
	s_waitcnt lgkmcnt(0)
	s_barrier
	s_setprio 1
	s_waitcnt lgkmcnt(0)
	v_mfma_f32_16x16x32_bf16 v[60:63], v[154:157], v[192:195], v[60:63]
	v_mfma_f32_16x16x32_bf16 v[56:59], v[162:165], v[192:195], v[56:59]
	v_mfma_f32_16x16x32_bf16 v[44:47], v[154:157], v[200:203], v[44:47]
	v_mfma_f32_16x16x32_bf16 v[40:43], v[162:165], v[200:203], v[40:43]
	v_mfma_f32_16x16x32_bf16 v[28:31], v[154:157], v[208:211], v[28:31]
	v_mfma_f32_16x16x32_bf16 v[24:27], v[162:165], v[208:211], v[24:27]
	v_mfma_f32_16x16x32_bf16 v[12:15], v[154:157], v[216:219], v[12:15]
	v_mfma_f32_16x16x32_bf16 v[8:11], v[162:165], v[216:219], v[8:11]
	v_mfma_f32_16x16x32_bf16 v[60:63], v[158:161], v[196:199], v[60:63]
	v_mfma_f32_16x16x32_bf16 v[56:59], v[172:175], v[196:199], v[56:59]
	v_mfma_f32_16x16x32_bf16 v[44:47], v[158:161], v[204:207], v[44:47]
	v_mfma_f32_16x16x32_bf16 v[40:43], v[172:175], v[204:207], v[40:43]
	v_mfma_f32_16x16x32_bf16 v[28:31], v[158:161], v[212:215], v[28:31]
	v_mfma_f32_16x16x32_bf16 v[24:27], v[172:175], v[212:215], v[24:27]
	v_mfma_f32_16x16x32_bf16 v[12:15], v[158:161], v[220:223], v[12:15]
	v_mfma_f32_16x16x32_bf16 v[8:11], v[172:175], v[220:223], v[8:11]
	v_mfma_f32_16x16x32_bf16 v[52:55], v[176:179], v[192:195], v[52:55]
	v_mfma_f32_16x16x32_bf16 v[48:51], v[184:187], v[192:195], v[48:51]
	v_mfma_f32_16x16x32_bf16 v[36:39], v[176:179], v[200:203], v[36:39]
	v_mfma_f32_16x16x32_bf16 v[32:35], v[184:187], v[200:203], v[32:35]
	v_mfma_f32_16x16x32_bf16 v[20:23], v[176:179], v[208:211], v[20:23]
	v_mfma_f32_16x16x32_bf16 v[16:19], v[184:187], v[208:211], v[16:19]
	v_mfma_f32_16x16x32_bf16 v[4:7], v[176:179], v[216:219], v[4:7]
	v_mfma_f32_16x16x32_bf16 v[0:3], v[184:187], v[216:219], v[0:3]
	v_mfma_f32_16x16x32_bf16 v[52:55], v[180:183], v[196:199], v[52:55]
	v_mfma_f32_16x16x32_bf16 v[48:51], v[188:191], v[196:199], v[48:51]
	v_mfma_f32_16x16x32_bf16 v[36:39], v[180:183], v[204:207], v[36:39]
	v_mfma_f32_16x16x32_bf16 v[32:35], v[188:191], v[204:207], v[32:35]
	v_mfma_f32_16x16x32_bf16 v[20:23], v[180:183], v[212:215], v[20:23]
	v_mfma_f32_16x16x32_bf16 v[16:19], v[188:191], v[212:215], v[16:19]
	v_mfma_f32_16x16x32_bf16 v[4:7], v[180:183], v[220:223], v[4:7]
	v_mfma_f32_16x16x32_bf16 v[0:3], v[188:191], v[220:223], v[0:3]
	s_setprio 0
	s_barrier
	s_add_i32 s57, 0, 0x18000
	v_add_u32_e32 v171, s57, v141
	s_add_i32 s58, 0, 0x1c000
	ds_read_b128 v[154:157], v171
	ds_read_b128 v[158:161], v171 offset:1024
	ds_read_b128 v[162:165], v171 offset:2048
	ds_read_b128 v[172:175], v171 offset:3072
	v_add_u32_e32 v171, s58, v141
	ds_read_b128 v[176:179], v171
	ds_read_b128 v[180:183], v171 offset:1024
	ds_read_b128 v[184:187], v171 offset:2048
	ds_read_b128 v[188:191], v171 offset:3072
	s_add_u32 s22, s22, 0x100000
	s_addc_u32 s23, s23, 0
	s_mov_b32 m0, s72
	ds_read_b128 v[192:195], v170 offset:32768
	ds_read_b128 v[196:199], v170 offset:33792
	ds_read_b128 v[200:203], v170 offset:34816
	ds_read_b128 v[204:207], v170 offset:35840
	ds_read_b128 v[208:211], v170 offset:36864
	ds_read_b128 v[212:215], v170 offset:37888
	ds_read_b128 v[216:219], v170 offset:38912
	ds_read_b128 v[220:223], v170 offset:39936
	global_load_lds_dwordx4 v128, s[22:23]
	s_mov_b32 m0, s73
	s_nop 0
	global_load_lds_dwordx4 v132, s[22:23]
	s_waitcnt vmcnt(8)
	s_waitcnt lgkmcnt(0)
	s_barrier
	s_setprio 1
	s_waitcnt lgkmcnt(0)
	v_mfma_f32_16x16x32_bf16 v[124:127], v[154:157], v[192:195], v[124:127]
	v_mfma_f32_16x16x32_bf16 v[120:123], v[162:165], v[192:195], v[120:123]
	v_mfma_f32_16x16x32_bf16 v[108:111], v[154:157], v[200:203], v[108:111]
	v_mfma_f32_16x16x32_bf16 v[104:107], v[162:165], v[200:203], v[104:107]
	v_mfma_f32_16x16x32_bf16 v[92:95], v[154:157], v[208:211], v[92:95]
	v_mfma_f32_16x16x32_bf16 v[88:91], v[162:165], v[208:211], v[88:91]
	v_mfma_f32_16x16x32_bf16 v[76:79], v[154:157], v[216:219], v[76:79]
	v_mfma_f32_16x16x32_bf16 v[72:75], v[162:165], v[216:219], v[72:75]
	v_mfma_f32_16x16x32_bf16 v[124:127], v[158:161], v[196:199], v[124:127]
	v_mfma_f32_16x16x32_bf16 v[120:123], v[172:175], v[196:199], v[120:123]
	v_mfma_f32_16x16x32_bf16 v[108:111], v[158:161], v[204:207], v[108:111]
	v_mfma_f32_16x16x32_bf16 v[104:107], v[172:175], v[204:207], v[104:107]
	v_mfma_f32_16x16x32_bf16 v[92:95], v[158:161], v[212:215], v[92:95]
	v_mfma_f32_16x16x32_bf16 v[88:91], v[172:175], v[212:215], v[88:91]
	v_mfma_f32_16x16x32_bf16 v[76:79], v[158:161], v[220:223], v[76:79]
	v_mfma_f32_16x16x32_bf16 v[72:75], v[172:175], v[220:223], v[72:75]
	v_mfma_f32_16x16x32_bf16 v[116:119], v[176:179], v[192:195], v[116:119]
	v_mfma_f32_16x16x32_bf16 v[112:115], v[184:187], v[192:195], v[112:115]
	v_mfma_f32_16x16x32_bf16 v[100:103], v[176:179], v[200:203], v[100:103]
	v_mfma_f32_16x16x32_bf16 v[96:99], v[184:187], v[200:203], v[96:99]
	v_mfma_f32_16x16x32_bf16 v[84:87], v[176:179], v[208:211], v[84:87]
	v_mfma_f32_16x16x32_bf16 v[80:83], v[184:187], v[208:211], v[80:83]
	v_mfma_f32_16x16x32_bf16 v[68:71], v[176:179], v[216:219], v[68:71]
	v_mfma_f32_16x16x32_bf16 v[64:67], v[184:187], v[216:219], v[64:67]
	v_mfma_f32_16x16x32_bf16 v[116:119], v[180:183], v[196:199], v[116:119]
	v_mfma_f32_16x16x32_bf16 v[112:115], v[188:191], v[196:199], v[112:115]
	v_mfma_f32_16x16x32_bf16 v[100:103], v[180:183], v[204:207], v[100:103]
	v_mfma_f32_16x16x32_bf16 v[96:99], v[188:191], v[204:207], v[96:99]
	v_mfma_f32_16x16x32_bf16 v[84:87], v[180:183], v[212:215], v[84:87]
	v_mfma_f32_16x16x32_bf16 v[80:83], v[188:191], v[212:215], v[80:83]
	v_mfma_f32_16x16x32_bf16 v[68:71], v[180:183], v[220:223], v[68:71]
	v_mfma_f32_16x16x32_bf16 v[64:67], v[188:191], v[220:223], v[64:67]
	s_setprio 0
	s_barrier
	s_add_i32 s22, s57, s93
	s_add_i32 m0, s22, 0xffffff80
	ds_read_b128 v[192:195], v170 offset:49152
	ds_read_b128 v[196:199], v170 offset:50176
	ds_read_b128 v[200:203], v170 offset:51200
	ds_read_b128 v[204:207], v170 offset:52224
	ds_read_b128 v[208:211], v170 offset:53248
	ds_read_b128 v[212:215], v170 offset:54272
	ds_read_b128 v[216:219], v170 offset:55296
	ds_read_b128 v[220:223], v170 offset:56320
	global_load_lds_dwordx4 v130, s[18:19] offset:128
	s_add_i32 m0, s22, 0x2000
	s_add_u32 s18, s18, 0x100080
	v_lshl_add_u64 v[166:167], v[224:225], 0, s[26:27]
	s_addc_u32 s19, s19, 0
	s_add_i32 s22, s58, s93
	global_load_lds_dwordx4 v[166:167], off
	s_mov_b32 m0, s22
	s_nop 0
	global_load_lds_dwordx4 v130, s[18:19]
	s_add_i32 m0, s22, 0x2000
	s_nop 0
	global_load_lds_dwordx4 v134, s[18:19]
	v_lshl_add_u64 v[166:167], v[226:227], 0, s[26:27]
	s_mov_b32 m0, s75
	s_nop 0
	global_load_lds_dwordx4 v[166:167], off
	v_lshl_add_u64 v[166:167], v[228:229], 0, s[26:27]
	s_mov_b32 m0, s76
	s_nop 0
	global_load_lds_dwordx4 v[166:167], off
	s_waitcnt vmcnt(8)
	s_waitcnt lgkmcnt(0)
	s_barrier
	s_setprio 1
	s_waitcnt lgkmcnt(0)
	v_mfma_f32_16x16x32_bf16 v[60:63], v[154:157], v[192:195], v[60:63]
	v_mfma_f32_16x16x32_bf16 v[56:59], v[162:165], v[192:195], v[56:59]
	v_mfma_f32_16x16x32_bf16 v[44:47], v[154:157], v[200:203], v[44:47]
	v_mfma_f32_16x16x32_bf16 v[40:43], v[162:165], v[200:203], v[40:43]
	v_mfma_f32_16x16x32_bf16 v[28:31], v[154:157], v[208:211], v[28:31]
	v_mfma_f32_16x16x32_bf16 v[24:27], v[162:165], v[208:211], v[24:27]
	v_mfma_f32_16x16x32_bf16 v[12:15], v[154:157], v[216:219], v[12:15]
	v_mfma_f32_16x16x32_bf16 v[8:11], v[162:165], v[216:219], v[8:11]
	v_mfma_f32_16x16x32_bf16 v[60:63], v[158:161], v[196:199], v[60:63]
	v_mfma_f32_16x16x32_bf16 v[56:59], v[172:175], v[196:199], v[56:59]
	v_mfma_f32_16x16x32_bf16 v[44:47], v[158:161], v[204:207], v[44:47]
	v_mfma_f32_16x16x32_bf16 v[40:43], v[172:175], v[204:207], v[40:43]
	v_mfma_f32_16x16x32_bf16 v[28:31], v[158:161], v[212:215], v[28:31]
	v_mfma_f32_16x16x32_bf16 v[24:27], v[172:175], v[212:215], v[24:27]
	v_mfma_f32_16x16x32_bf16 v[12:15], v[158:161], v[220:223], v[12:15]
	v_mfma_f32_16x16x32_bf16 v[8:11], v[172:175], v[220:223], v[8:11]
	v_mfma_f32_16x16x32_bf16 v[52:55], v[176:179], v[192:195], v[52:55]
	v_mfma_f32_16x16x32_bf16 v[48:51], v[184:187], v[192:195], v[48:51]
	v_mfma_f32_16x16x32_bf16 v[36:39], v[176:179], v[200:203], v[36:39]
	v_mfma_f32_16x16x32_bf16 v[32:35], v[184:187], v[200:203], v[32:35]
	v_mfma_f32_16x16x32_bf16 v[20:23], v[176:179], v[208:211], v[20:23]
	v_mfma_f32_16x16x32_bf16 v[16:19], v[184:187], v[208:211], v[16:19]
	v_mfma_f32_16x16x32_bf16 v[4:7], v[176:179], v[216:219], v[4:7]
	v_mfma_f32_16x16x32_bf16 v[0:3], v[184:187], v[216:219], v[0:3]
	v_mfma_f32_16x16x32_bf16 v[52:55], v[180:183], v[196:199], v[52:55]
	v_mfma_f32_16x16x32_bf16 v[48:51], v[188:191], v[196:199], v[48:51]
	v_mfma_f32_16x16x32_bf16 v[36:39], v[180:183], v[204:207], v[36:39]
	v_mfma_f32_16x16x32_bf16 v[32:35], v[188:191], v[204:207], v[32:35]
	v_mfma_f32_16x16x32_bf16 v[20:23], v[180:183], v[212:215], v[20:23]
	v_mfma_f32_16x16x32_bf16 v[16:19], v[188:191], v[212:215], v[16:19]
	v_mfma_f32_16x16x32_bf16 v[4:7], v[180:183], v[220:223], v[4:7]
	v_mfma_f32_16x16x32_bf16 v[0:3], v[188:191], v[220:223], v[0:3]
	s_setprio 0
	s_barrier
	s_add_i32 s56, s56, 2
	s_add_u32 s16, s16, 0x100
	s_addc_u32 s17, s17, 0
	s_add_u32 s49, s49, 0x100
	s_addc_u32 s51, s51, 0
	s_cmp_lt_u32 s56, 62
	s_cbranch_scc1 .LBB0_124
	s_andn2_b64 vcc, exec, s[94:95]
	s_cbranch_vccnz .LBB0_127
	s_barrier

.LBB0_1154:
	ds_read_b128 v[140:143], v157
	ds_read_b128 v[144:147], v157 offset:1024
	s_waitcnt lgkmcnt(0)
	ds_read_b128 v[148:151], v157 offset:2048
	ds_read_b128 v[162:165], v157 offset:3072
	ds_read_b128 v[166:169], v158
	ds_read_b128 v[170:173], v158 offset:1024
	ds_read_b128 v[174:177], v158 offset:2048
	ds_read_b128 v[178:181], v158 offset:3072
	s_add_i32 s72, s46, 2
	s_add_u32 s47, s44, 0xfff00080
	s_addc_u32 s48, s45, -1
	s_cmp_eq_u32 s75, s46
	s_cselect_b32 s46, s43, s76
	s_cselect_b32 s49, s29, s48
	s_cselect_b32 s48, s35, s47
	s_cselect_b32 s47, s31, s77
	s_add_i32 m0, s53, 0xc000
	ds_read_b128 v[182:185], v159
	ds_read_b128 v[186:189], v159 offset:1024
	ds_read_b128 v[190:193], v159 offset:2048
	ds_read_b128 v[194:197], v159 offset:3072
	ds_read_b128 v[198:201], v159 offset:4096
	ds_read_b128 v[202:205], v159 offset:5120
	ds_read_b128 v[206:209], v159 offset:6144
	ds_read_b128 v[210:213], v159 offset:7168
	global_load_lds_dwordx4 v134, s[44:45]
	s_add_i32 m0, s53, 0xe000
	s_nop 0
	global_load_lds_dwordx4 v136, s[44:45]
	s_waitcnt vmcnt(8)
	s_waitcnt lgkmcnt(0)
	s_barrier
	s_setprio 1
	s_waitcnt lgkmcnt(0)
	v_mfma_f32_16x16x32_bf16 v[124:127], v[140:143], v[182:185], v[124:127]
	v_mfma_f32_16x16x32_bf16 v[120:123], v[148:151], v[182:185], v[120:123]
	v_mfma_f32_16x16x32_bf16 v[116:119], v[140:143], v[190:193], v[116:119]
	v_mfma_f32_16x16x32_bf16 v[108:111], v[148:151], v[190:193], v[108:111]
	v_mfma_f32_16x16x32_bf16 v[100:103], v[140:143], v[198:201], v[100:103]
	v_mfma_f32_16x16x32_bf16 v[92:95], v[148:151], v[198:201], v[92:95]
	v_mfma_f32_16x16x32_bf16 v[84:87], v[140:143], v[206:209], v[84:87]
	v_mfma_f32_16x16x32_bf16 v[76:79], v[148:151], v[206:209], v[76:79]
	v_mfma_f32_16x16x32_bf16 v[124:127], v[144:147], v[186:189], v[124:127]
	v_mfma_f32_16x16x32_bf16 v[120:123], v[162:165], v[186:189], v[120:123]
	v_mfma_f32_16x16x32_bf16 v[116:119], v[144:147], v[194:197], v[116:119]
	v_mfma_f32_16x16x32_bf16 v[108:111], v[162:165], v[194:197], v[108:111]
	v_mfma_f32_16x16x32_bf16 v[100:103], v[144:147], v[202:205], v[100:103]
	v_mfma_f32_16x16x32_bf16 v[92:95], v[162:165], v[202:205], v[92:95]
	v_mfma_f32_16x16x32_bf16 v[84:87], v[144:147], v[210:213], v[84:87]
	v_mfma_f32_16x16x32_bf16 v[76:79], v[162:165], v[210:213], v[76:79]
	v_mfma_f32_16x16x32_bf16 v[112:115], v[166:169], v[182:185], v[112:115]
	v_mfma_f32_16x16x32_bf16 v[104:107], v[174:177], v[182:185], v[104:107]
	v_mfma_f32_16x16x32_bf16 v[96:99], v[166:169], v[190:193], v[96:99]
	v_mfma_f32_16x16x32_bf16 v[88:91], v[174:177], v[190:193], v[88:91]
	v_mfma_f32_16x16x32_bf16 v[80:83], v[166:169], v[198:201], v[80:83]
	v_mfma_f32_16x16x32_bf16 v[72:75], v[174:177], v[198:201], v[72:75]
	v_mfma_f32_16x16x32_bf16 v[68:71], v[166:169], v[206:209], v[68:71]
	v_mfma_f32_16x16x32_bf16 v[64:67], v[174:177], v[206:209], v[64:67]
	v_mfma_f32_16x16x32_bf16 v[112:115], v[170:173], v[186:189], v[112:115]
	v_mfma_f32_16x16x32_bf16 v[104:107], v[178:181], v[186:189], v[104:107]
	v_mfma_f32_16x16x32_bf16 v[96:99], v[170:173], v[194:197], v[96:99]
	v_mfma_f32_16x16x32_bf16 v[88:91], v[178:181], v[194:197], v[88:91]
	v_mfma_f32_16x16x32_bf16 v[80:83], v[170:173], v[202:205], v[80:83]
	v_mfma_f32_16x16x32_bf16 v[72:75], v[178:181], v[202:205], v[72:75]
	v_mfma_f32_16x16x32_bf16 v[68:71], v[170:173], v[210:213], v[68:71]
	v_mfma_f32_16x16x32_bf16 v[64:67], v[178:181], v[210:213], v[64:67]
	s_setprio 0
	s_barrier
	s_add_i32 s78, s62, s93
	s_mov_b32 m0, s78
	ds_read_b128 v[182:185], v159 offset:16384
	ds_read_b128 v[186:189], v159 offset:17408
	ds_read_b128 v[190:193], v159 offset:18432
	ds_read_b128 v[194:197], v159 offset:19456
	ds_read_b128 v[198:201], v159 offset:20480
	ds_read_b128 v[202:205], v159 offset:21504
	ds_read_b128 v[206:209], v159 offset:22528
	ds_read_b128 v[210:213], v159 offset:23552
	global_load_lds_dwordx4 v128, s[46:47]
	s_add_i32 m0, s78, 0x2000
	s_add_u32 s78, s46, 0x100000
	v_lshl_add_u64 v[216:217], s[46:47], 0, v[130:131]
	s_addc_u32 s79, s47, 0
	s_add_i32 s80, s63, s93
	global_load_lds_dwordx4 v130, s[46:47]
	s_mov_b32 m0, s80
	v_lshl_add_u64 v[220:221], s[48:49], 0, v[130:131]
	global_load_lds_dwordx4 v128, s[78:79]
	s_add_i32 m0, s80, 0x2000
	s_nop 0
	global_load_lds_dwordx4 v130, s[78:79]
	v_lshl_add_u64 v[218:219], s[48:49], 0, v[128:129]
	s_mov_b32 m0, s53
	s_nop 0
	global_load_lds_dwordx4 v128, s[48:49]
	s_mov_b32 m0, s54
	s_nop 0
	global_load_lds_dwordx4 v130, s[48:49]
	s_waitcnt vmcnt(8)
	s_waitcnt lgkmcnt(0)
	s_barrier
	s_setprio 1
	s_waitcnt lgkmcnt(0)
	v_mfma_f32_16x16x32_bf16 v[60:63], v[140:143], v[182:185], v[60:63]
	v_mfma_f32_16x16x32_bf16 v[56:59], v[148:151], v[182:185], v[56:59]
	v_mfma_f32_16x16x32_bf16 v[52:55], v[140:143], v[190:193], v[52:55]
	v_mfma_f32_16x16x32_bf16 v[40:43], v[148:151], v[190:193], v[40:43]
	v_mfma_f32_16x16x32_bf16 v[36:39], v[140:143], v[198:201], v[36:39]
	v_mfma_f32_16x16x32_bf16 v[24:27], v[148:151], v[198:201], v[24:27]
	v_mfma_f32_16x16x32_bf16 v[20:23], v[140:143], v[206:209], v[20:23]
	v_mfma_f32_16x16x32_bf16 v[8:11], v[148:151], v[206:209], v[8:11]
	v_mfma_f32_16x16x32_bf16 v[60:63], v[144:147], v[186:189], v[60:63]
	v_mfma_f32_16x16x32_bf16 v[56:59], v[162:165], v[186:189], v[56:59]
	v_mfma_f32_16x16x32_bf16 v[52:55], v[144:147], v[194:197], v[52:55]
	v_mfma_f32_16x16x32_bf16 v[40:43], v[162:165], v[194:197], v[40:43]
	v_mfma_f32_16x16x32_bf16 v[36:39], v[144:147], v[202:205], v[36:39]
	v_mfma_f32_16x16x32_bf16 v[24:27], v[162:165], v[202:205], v[24:27]
	v_mfma_f32_16x16x32_bf16 v[20:23], v[144:147], v[210:213], v[20:23]
	v_mfma_f32_16x16x32_bf16 v[8:11], v[162:165], v[210:213], v[8:11]
	v_mfma_f32_16x16x32_bf16 v[48:51], v[166:169], v[182:185], v[48:51]
	v_mfma_f32_16x16x32_bf16 v[44:47], v[174:177], v[182:185], v[44:47]
	v_mfma_f32_16x16x32_bf16 v[32:35], v[166:169], v[190:193], v[32:35]
	v_mfma_f32_16x16x32_bf16 v[28:31], v[174:177], v[190:193], v[28:31]
	v_mfma_f32_16x16x32_bf16 v[16:19], v[166:169], v[198:201], v[16:19]
	v_mfma_f32_16x16x32_bf16 v[12:15], v[174:177], v[198:201], v[12:15]
	v_mfma_f32_16x16x32_bf16 v[4:7], v[166:169], v[206:209], v[4:7]
	v_mfma_f32_16x16x32_bf16 v[0:3], v[174:177], v[206:209], v[0:3]
	v_mfma_f32_16x16x32_bf16 v[48:51], v[170:173], v[186:189], v[48:51]
	v_mfma_f32_16x16x32_bf16 v[44:47], v[178:181], v[186:189], v[44:47]
	v_mfma_f32_16x16x32_bf16 v[32:35], v[170:173], v[194:197], v[32:35]
	v_mfma_f32_16x16x32_bf16 v[28:31], v[178:181], v[194:197], v[28:31]
	v_mfma_f32_16x16x32_bf16 v[16:19], v[170:173], v[202:205], v[16:19]
	v_mfma_f32_16x16x32_bf16 v[12:15], v[178:181], v[202:205], v[12:15]
	v_mfma_f32_16x16x32_bf16 v[4:7], v[170:173], v[210:213], v[4:7]
	v_mfma_f32_16x16x32_bf16 v[0:3], v[178:181], v[210:213], v[0:3]
	s_setprio 0
	s_barrier
	s_add_i32 s78, 0, 0x18000
	v_add_u32_e32 v133, s78, v153
	s_add_i32 s79, 0, 0x1c000
	ds_read_b128 v[140:143], v133
	ds_read_b128 v[144:147], v133 offset:1024
	ds_read_b128 v[148:151], v133 offset:2048
	ds_read_b128 v[162:165], v133 offset:3072
	v_add_u32_e32 v133, s79, v153
	ds_read_b128 v[166:169], v133
	ds_read_b128 v[170:173], v133 offset:1024
	ds_read_b128 v[174:177], v133 offset:2048
	ds_read_b128 v[178:181], v133 offset:3072
	s_add_u32 s48, s48, 0x100000
	s_addc_u32 s49, s49, 0
	s_mov_b32 m0, s55
	ds_read_b128 v[182:185], v159 offset:32768
	ds_read_b128 v[186:189], v159 offset:33792
	ds_read_b128 v[190:193], v159 offset:34816
	ds_read_b128 v[194:197], v159 offset:35840
	ds_read_b128 v[198:201], v159 offset:36864
	ds_read_b128 v[202:205], v159 offset:37888
	ds_read_b128 v[206:209], v159 offset:38912
	ds_read_b128 v[210:213], v159 offset:39936
	global_load_lds_dwordx4 v128, s[48:49]
	s_mov_b32 m0, s56
	s_nop 0
	global_load_lds_dwordx4 v130, s[48:49]
	s_waitcnt vmcnt(8)
	s_waitcnt lgkmcnt(0)
	s_barrier
	s_setprio 1
	s_waitcnt lgkmcnt(0)
	v_mfma_f32_16x16x32_bf16 v[124:127], v[140:143], v[182:185], v[124:127]
	v_mfma_f32_16x16x32_bf16 v[120:123], v[148:151], v[182:185], v[120:123]
	v_mfma_f32_16x16x32_bf16 v[116:119], v[140:143], v[190:193], v[116:119]
	v_mfma_f32_16x16x32_bf16 v[108:111], v[148:151], v[190:193], v[108:111]
	v_mfma_f32_16x16x32_bf16 v[100:103], v[140:143], v[198:201], v[100:103]
	v_mfma_f32_16x16x32_bf16 v[92:95], v[148:151], v[198:201], v[92:95]
	v_mfma_f32_16x16x32_bf16 v[84:87], v[140:143], v[206:209], v[84:87]
	v_mfma_f32_16x16x32_bf16 v[76:79], v[148:151], v[206:209], v[76:79]
	v_mfma_f32_16x16x32_bf16 v[124:127], v[144:147], v[186:189], v[124:127]
	v_mfma_f32_16x16x32_bf16 v[120:123], v[162:165], v[186:189], v[120:123]
	v_mfma_f32_16x16x32_bf16 v[116:119], v[144:147], v[194:197], v[116:119]
	v_mfma_f32_16x16x32_bf16 v[108:111], v[162:165], v[194:197], v[108:111]
	v_mfma_f32_16x16x32_bf16 v[100:103], v[144:147], v[202:205], v[100:103]
	v_mfma_f32_16x16x32_bf16 v[92:95], v[162:165], v[202:205], v[92:95]
	v_mfma_f32_16x16x32_bf16 v[84:87], v[144:147], v[210:213], v[84:87]
	v_mfma_f32_16x16x32_bf16 v[76:79], v[162:165], v[210:213], v[76:79]
	v_mfma_f32_16x16x32_bf16 v[112:115], v[166:169], v[182:185], v[112:115]
	v_mfma_f32_16x16x32_bf16 v[104:107], v[174:177], v[182:185], v[104:107]
	v_mfma_f32_16x16x32_bf16 v[96:99], v[166:169], v[190:193], v[96:99]
	v_mfma_f32_16x16x32_bf16 v[88:91], v[174:177], v[190:193], v[88:91]
	v_mfma_f32_16x16x32_bf16 v[80:83], v[166:169], v[198:201], v[80:83]
	v_mfma_f32_16x16x32_bf16 v[72:75], v[174:177], v[198:201], v[72:75]
	v_mfma_f32_16x16x32_bf16 v[68:71], v[166:169], v[206:209], v[68:71]
	v_mfma_f32_16x16x32_bf16 v[64:67], v[174:177], v[206:209], v[64:67]
	v_mfma_f32_16x16x32_bf16 v[112:115], v[170:173], v[186:189], v[112:115]
	v_mfma_f32_16x16x32_bf16 v[104:107], v[178:181], v[186:189], v[104:107]
	v_mfma_f32_16x16x32_bf16 v[96:99], v[170:173], v[194:197], v[96:99]
	v_mfma_f32_16x16x32_bf16 v[88:91], v[178:181], v[194:197], v[88:91]
	v_mfma_f32_16x16x32_bf16 v[80:83], v[170:173], v[202:205], v[80:83]
	v_mfma_f32_16x16x32_bf16 v[72:75], v[178:181], v[202:205], v[72:75]
	v_mfma_f32_16x16x32_bf16 v[68:71], v[170:173], v[210:213], v[68:71]
	v_mfma_f32_16x16x32_bf16 v[64:67], v[178:181], v[210:213], v[64:67]
	s_setprio 0
	s_barrier
	s_add_i32 s48, s78, s93
	s_add_i32 m0, s48, 0xffffff80
	ds_read_b128 v[182:185], v159 offset:49152
	ds_read_b128 v[186:189], v159 offset:50176
	ds_read_b128 v[190:193], v159 offset:51200
	ds_read_b128 v[194:197], v159 offset:52224
	ds_read_b128 v[198:201], v159 offset:53248
	ds_read_b128 v[202:205], v159 offset:54272
	ds_read_b128 v[206:209], v159 offset:55296
	ds_read_b128 v[210:213], v159 offset:56320
	global_load_lds_dwordx4 v128, s[46:47] offset:128
	s_add_i32 m0, s48, 0x2000
	s_add_u32 s46, s46, 0x100080
	v_lshl_add_u64 v[214:215], v[216:217], 0, s[18:19]
	s_addc_u32 s47, s47, 0
	s_add_i32 s48, s79, s93
	global_load_lds_dwordx4 v[214:215], off
	s_mov_b32 m0, s48
	s_nop 0
	global_load_lds_dwordx4 v128, s[46:47]
	s_add_i32 m0, s48, 0x2000
	s_nop 0
	global_load_lds_dwordx4 v130, s[46:47]
	v_lshl_add_u64 v[214:215], v[218:219], 0, s[18:19]
	s_mov_b32 m0, s60
	s_nop 0
	global_load_lds_dwordx4 v[214:215], off
	v_lshl_add_u64 v[214:215], v[220:221], 0, s[18:19]
	s_mov_b32 m0, s61
	s_nop 0
	global_load_lds_dwordx4 v[214:215], off
	s_waitcnt vmcnt(8)
	s_waitcnt lgkmcnt(0)
	s_barrier
	s_setprio 1
	s_waitcnt lgkmcnt(0)
	v_mfma_f32_16x16x32_bf16 v[60:63], v[140:143], v[182:185], v[60:63]
	v_mfma_f32_16x16x32_bf16 v[56:59], v[148:151], v[182:185], v[56:59]
	v_mfma_f32_16x16x32_bf16 v[52:55], v[140:143], v[190:193], v[52:55]
	v_mfma_f32_16x16x32_bf16 v[40:43], v[148:151], v[190:193], v[40:43]
	v_mfma_f32_16x16x32_bf16 v[36:39], v[140:143], v[198:201], v[36:39]
	v_mfma_f32_16x16x32_bf16 v[24:27], v[148:151], v[198:201], v[24:27]
	v_mfma_f32_16x16x32_bf16 v[20:23], v[140:143], v[206:209], v[20:23]
	v_mfma_f32_16x16x32_bf16 v[8:11], v[148:151], v[206:209], v[8:11]
	v_mfma_f32_16x16x32_bf16 v[60:63], v[144:147], v[186:189], v[60:63]
	v_mfma_f32_16x16x32_bf16 v[56:59], v[162:165], v[186:189], v[56:59]
	v_mfma_f32_16x16x32_bf16 v[52:55], v[144:147], v[194:197], v[52:55]
	v_mfma_f32_16x16x32_bf16 v[40:43], v[162:165], v[194:197], v[40:43]
	v_mfma_f32_16x16x32_bf16 v[36:39], v[144:147], v[202:205], v[36:39]
	v_mfma_f32_16x16x32_bf16 v[24:27], v[162:165], v[202:205], v[24:27]
	v_mfma_f32_16x16x32_bf16 v[20:23], v[144:147], v[210:213], v[20:23]
	v_mfma_f32_16x16x32_bf16 v[8:11], v[162:165], v[210:213], v[8:11]
	v_mfma_f32_16x16x32_bf16 v[48:51], v[166:169], v[182:185], v[48:51]
	v_mfma_f32_16x16x32_bf16 v[44:47], v[174:177], v[182:185], v[44:47]
	v_mfma_f32_16x16x32_bf16 v[32:35], v[166:169], v[190:193], v[32:35]
	v_mfma_f32_16x16x32_bf16 v[28:31], v[174:177], v[190:193], v[28:31]
	v_mfma_f32_16x16x32_bf16 v[16:19], v[166:169], v[198:201], v[16:19]
	v_mfma_f32_16x16x32_bf16 v[12:15], v[174:177], v[198:201], v[12:15]
	v_mfma_f32_16x16x32_bf16 v[4:7], v[166:169], v[206:209], v[4:7]
	v_mfma_f32_16x16x32_bf16 v[0:3], v[174:177], v[206:209], v[0:3]
	v_mfma_f32_16x16x32_bf16 v[48:51], v[170:173], v[186:189], v[48:51]
	v_mfma_f32_16x16x32_bf16 v[44:47], v[178:181], v[186:189], v[44:47]
	v_mfma_f32_16x16x32_bf16 v[32:35], v[170:173], v[194:197], v[32:35]
	v_mfma_f32_16x16x32_bf16 v[28:31], v[178:181], v[194:197], v[28:31]
	v_mfma_f32_16x16x32_bf16 v[16:19], v[170:173], v[202:205], v[16:19]
	v_mfma_f32_16x16x32_bf16 v[12:15], v[178:181], v[202:205], v[12:15]
	v_mfma_f32_16x16x32_bf16 v[4:7], v[170:173], v[210:213], v[4:7]
	v_mfma_f32_16x16x32_bf16 v[0:3], v[178:181], v[210:213], v[0:3]
	s_setprio 0
	s_barrier
	s_add_u32 s44, s44, 0x100
	s_addc_u32 s45, s45, 0
	s_add_u32 s76, s76, 0x100
	s_addc_u32 s77, s77, 0
	s_cmp_lt_i32 s72, s27
	s_mov_b32 s46, s72
	s_cbranch_scc1 .LBB0_1154
	s_andn2_b64 vcc, exec, s[94:95]
	s_cbranch_vccnz .LBB0_1157
	s_barrier

.LBB0_1297:
	v_add_u32_e32 v154, s80, v181
	v_add_u32_e32 v170, s81, v181
	ds_read_b128 v[142:145], v154
	ds_read_b128 v[146:149], v154 offset:1024
	ds_read_b128 v[150:153], v154 offset:2048
	ds_read_b128 v[154:157], v154 offset:3072
	ds_read_b128 v[158:161], v170
	ds_read_b128 v[162:165], v170 offset:1024
	ds_read_b128 v[166:169], v170 offset:2048
	ds_read_b128 v[170:173], v170 offset:3072
	s_add_i32 s72, s62, 2
	s_add_u32 s24, s60, 0xfff80080
	s_addc_u32 s25, s61, -1
	s_cmp_eq_u32 s97, s62
	s_cselect_b32 s62, s96, vcc_lo
	s_cselect_b32 s65, s41, s25
	s_cselect_b32 s64, s45, s24
	s_cselect_b32 s63, s43, vcc_hi
	s_add_i32 m0, s55, 0xc000
	ds_read_b128 v[174:177], v183
	ds_read_b128 v[184:187], v183 offset:1024
	ds_read_b128 v[188:191], v183 offset:2048
	ds_read_b128 v[192:195], v183 offset:3072
	ds_read_b128 v[196:199], v183 offset:4096
	ds_read_b128 v[200:203], v183 offset:5120
	ds_read_b128 v[204:207], v183 offset:6144
	ds_read_b128 v[208:211], v183 offset:7168
	global_load_lds_dwordx4 v138, s[60:61]
	s_add_i32 m0, s55, 0xe000
	s_nop 0
	global_load_lds_dwordx4 v140, s[60:61]
	s_waitcnt vmcnt(8)
	s_waitcnt lgkmcnt(0)
	s_barrier
	s_setprio 1
	s_waitcnt lgkmcnt(0)
	v_mfma_i32_16x16x64_i8 v[124:127], v[142:145], v[174:177], v[124:127]
	v_mfma_i32_16x16x64_i8 v[120:123], v[150:153], v[174:177], v[120:123]
	v_mfma_i32_16x16x64_i8 v[116:119], v[142:145], v[188:191], v[116:119]
	v_mfma_i32_16x16x64_i8 v[112:115], v[150:153], v[188:191], v[112:115]
	v_mfma_i32_16x16x64_i8 v[104:107], v[142:145], v[196:199], v[104:107]
	v_mfma_i32_16x16x64_i8 v[96:99], v[150:153], v[196:199], v[96:99]
	v_mfma_i32_16x16x64_i8 v[88:91], v[142:145], v[204:207], v[88:91]
	v_mfma_i32_16x16x64_i8 v[80:83], v[150:153], v[204:207], v[80:83]
	v_mfma_i32_16x16x64_i8 v[124:127], v[146:149], v[184:187], v[124:127]
	v_mfma_i32_16x16x64_i8 v[120:123], v[154:157], v[184:187], v[120:123]
	v_mfma_i32_16x16x64_i8 v[116:119], v[146:149], v[192:195], v[116:119]
	v_mfma_i32_16x16x64_i8 v[112:115], v[154:157], v[192:195], v[112:115]
	v_mfma_i32_16x16x64_i8 v[104:107], v[146:149], v[200:203], v[104:107]
	v_mfma_i32_16x16x64_i8 v[96:99], v[154:157], v[200:203], v[96:99]
	v_mfma_i32_16x16x64_i8 v[88:91], v[146:149], v[208:211], v[88:91]
	v_mfma_i32_16x16x64_i8 v[80:83], v[154:157], v[208:211], v[80:83]
	v_mfma_i32_16x16x64_i8 v[108:111], v[158:161], v[174:177], v[108:111]
	v_mfma_i32_16x16x64_i8 v[100:103], v[166:169], v[174:177], v[100:103]
	v_mfma_i32_16x16x64_i8 v[92:95], v[158:161], v[188:191], v[92:95]
	v_mfma_i32_16x16x64_i8 v[84:87], v[166:169], v[188:191], v[84:87]
	v_mfma_i32_16x16x64_i8 v[76:79], v[158:161], v[196:199], v[76:79]
	v_mfma_i32_16x16x64_i8 v[72:75], v[166:169], v[196:199], v[72:75]
	v_mfma_i32_16x16x64_i8 v[68:71], v[158:161], v[204:207], v[68:71]
	v_mfma_i32_16x16x64_i8 v[64:67], v[166:169], v[204:207], v[64:67]
	v_mfma_i32_16x16x64_i8 v[108:111], v[162:165], v[184:187], v[108:111]
	v_mfma_i32_16x16x64_i8 v[100:103], v[170:173], v[184:187], v[100:103]
	v_mfma_i32_16x16x64_i8 v[92:95], v[162:165], v[192:195], v[92:95]
	v_mfma_i32_16x16x64_i8 v[84:87], v[170:173], v[192:195], v[84:87]
	v_mfma_i32_16x16x64_i8 v[76:79], v[162:165], v[200:203], v[76:79]
	v_mfma_i32_16x16x64_i8 v[72:75], v[170:173], v[200:203], v[72:75]
	v_mfma_i32_16x16x64_i8 v[68:71], v[162:165], v[208:211], v[68:71]
	v_mfma_i32_16x16x64_i8 v[64:67], v[170:173], v[208:211], v[64:67]
	s_setprio 0
	s_barrier
	s_add_i32 s24, s80, s93
	s_mov_b32 m0, s24
	ds_read_b128 v[174:177], v183 offset:16384
	ds_read_b128 v[184:187], v183 offset:17408
	ds_read_b128 v[188:191], v183 offset:18432
	ds_read_b128 v[192:195], v183 offset:19456
	ds_read_b128 v[196:199], v183 offset:20480
	ds_read_b128 v[200:203], v183 offset:21504
	ds_read_b128 v[204:207], v183 offset:22528
	ds_read_b128 v[208:211], v183 offset:23552
	global_load_lds_dwordx4 v130, s[62:63]
	s_add_i32 m0, s24, 0x2000
	s_add_u32 s24, s62, 0x80000
	v_lshl_add_u64 v[212:213], s[62:63], 0, v[134:135]
	s_addc_u32 s25, s63, 0
	s_add_i32 s73, s81, s93
	global_load_lds_dwordx4 v134, s[62:63]
	s_mov_b32 m0, s73
	s_nop 0
	global_load_lds_dwordx4 v130, s[24:25]
	s_add_i32 m0, s73, 0x2000
	s_nop 0
	global_load_lds_dwordx4 v134, s[24:25]
	s_mov_b32 m0, s55
	s_nop 0
	global_load_lds_dwordx4 v128, s[64:65]
	s_mov_b32 m0, s57
	s_nop 0
	global_load_lds_dwordx4 v132, s[64:65]
	s_waitcnt vmcnt(8)
	s_waitcnt lgkmcnt(0)
	s_barrier
	s_setprio 1
	s_waitcnt lgkmcnt(0)
	v_mfma_i32_16x16x64_i8 v[60:63], v[142:145], v[174:177], v[60:63]
	v_mfma_i32_16x16x64_i8 v[56:59], v[150:153], v[174:177], v[56:59]
	v_mfma_i32_16x16x64_i8 v[52:55], v[142:145], v[188:191], v[52:55]
	v_mfma_i32_16x16x64_i8 v[48:51], v[150:153], v[188:191], v[48:51]
	v_mfma_i32_16x16x64_i8 v[44:47], v[142:145], v[196:199], v[44:47]
	v_mfma_i32_16x16x64_i8 v[40:43], v[150:153], v[196:199], v[40:43]
	v_mfma_i32_16x16x64_i8 v[36:39], v[142:145], v[204:207], v[36:39]
	v_mfma_i32_16x16x64_i8 v[32:35], v[150:153], v[204:207], v[32:35]
	v_mfma_i32_16x16x64_i8 v[60:63], v[146:149], v[184:187], v[60:63]
	v_mfma_i32_16x16x64_i8 v[56:59], v[154:157], v[184:187], v[56:59]
	v_mfma_i32_16x16x64_i8 v[52:55], v[146:149], v[192:195], v[52:55]
	v_mfma_i32_16x16x64_i8 v[48:51], v[154:157], v[192:195], v[48:51]
	v_mfma_i32_16x16x64_i8 v[44:47], v[146:149], v[200:203], v[44:47]
	v_mfma_i32_16x16x64_i8 v[40:43], v[154:157], v[200:203], v[40:43]
	v_mfma_i32_16x16x64_i8 v[36:39], v[146:149], v[208:211], v[36:39]
	v_mfma_i32_16x16x64_i8 v[32:35], v[154:157], v[208:211], v[32:35]
	v_mfma_i32_16x16x64_i8 v[28:31], v[158:161], v[174:177], v[28:31]
	v_mfma_i32_16x16x64_i8 v[24:27], v[166:169], v[174:177], v[24:27]
	v_mfma_i32_16x16x64_i8 v[20:23], v[158:161], v[188:191], v[20:23]
	v_mfma_i32_16x16x64_i8 v[16:19], v[166:169], v[188:191], v[16:19]
	v_mfma_i32_16x16x64_i8 v[12:15], v[158:161], v[196:199], v[12:15]
	v_mfma_i32_16x16x64_i8 v[8:11], v[166:169], v[196:199], v[8:11]
	v_mfma_i32_16x16x64_i8 v[4:7], v[158:161], v[204:207], v[4:7]
	v_mfma_i32_16x16x64_i8 v[0:3], v[166:169], v[204:207], v[0:3]
	v_mfma_i32_16x16x64_i8 v[28:31], v[162:165], v[184:187], v[28:31]
	v_mfma_i32_16x16x64_i8 v[24:27], v[170:173], v[184:187], v[24:27]
	v_mfma_i32_16x16x64_i8 v[20:23], v[162:165], v[192:195], v[20:23]
	v_mfma_i32_16x16x64_i8 v[16:19], v[170:173], v[192:195], v[16:19]
	v_mfma_i32_16x16x64_i8 v[12:15], v[162:165], v[200:203], v[12:15]
	v_mfma_i32_16x16x64_i8 v[8:11], v[170:173], v[200:203], v[8:11]
	v_mfma_i32_16x16x64_i8 v[4:7], v[162:165], v[208:211], v[4:7]
	v_mfma_i32_16x16x64_i8 v[0:3], v[170:173], v[208:211], v[0:3]
	s_setprio 0
	s_barrier
	s_add_i32 s73, 0, 0x18000
	s_add_i32 s66, 0, 0x1c000
	v_add_u32_e32 v154, s73, v181
	v_add_u32_e32 v170, s66, v181
	ds_read_b128 v[142:145], v154
	ds_read_b128 v[146:149], v154 offset:1024
	ds_read_b128 v[150:153], v154 offset:2048
	ds_read_b128 v[154:157], v154 offset:3072
	ds_read_b128 v[158:161], v170
	ds_read_b128 v[162:165], v170 offset:1024
	ds_read_b128 v[166:169], v170 offset:2048
	ds_read_b128 v[170:173], v170 offset:3072
	s_add_u32 s24, s64, 0x80000
	s_addc_u32 s25, s65, 0
	s_mov_b32 m0, s69
	ds_read_b128 v[174:177], v183 offset:32768
	ds_read_b128 v[184:187], v183 offset:33792
	ds_read_b128 v[188:191], v183 offset:34816
	ds_read_b128 v[192:195], v183 offset:35840
	ds_read_b128 v[196:199], v183 offset:36864
	ds_read_b128 v[200:203], v183 offset:37888
	ds_read_b128 v[204:207], v183 offset:38912
	ds_read_b128 v[208:211], v183 offset:39936
	global_load_lds_dwordx4 v128, s[24:25]
	s_mov_b32 m0, s74
	s_nop 0
	global_load_lds_dwordx4 v132, s[24:25]
	s_waitcnt vmcnt(8)
	s_waitcnt lgkmcnt(0)
	s_barrier
	s_setprio 1
	s_waitcnt lgkmcnt(0)
	v_mfma_i32_16x16x64_i8 v[124:127], v[142:145], v[174:177], v[124:127]
	v_mfma_i32_16x16x64_i8 v[120:123], v[150:153], v[174:177], v[120:123]
	v_mfma_i32_16x16x64_i8 v[116:119], v[142:145], v[188:191], v[116:119]
	v_mfma_i32_16x16x64_i8 v[112:115], v[150:153], v[188:191], v[112:115]
	v_mfma_i32_16x16x64_i8 v[104:107], v[142:145], v[196:199], v[104:107]
	v_mfma_i32_16x16x64_i8 v[96:99], v[150:153], v[196:199], v[96:99]
	v_mfma_i32_16x16x64_i8 v[88:91], v[142:145], v[204:207], v[88:91]
	v_mfma_i32_16x16x64_i8 v[80:83], v[150:153], v[204:207], v[80:83]
	v_mfma_i32_16x16x64_i8 v[124:127], v[146:149], v[184:187], v[124:127]
	v_mfma_i32_16x16x64_i8 v[120:123], v[154:157], v[184:187], v[120:123]
	v_mfma_i32_16x16x64_i8 v[116:119], v[146:149], v[192:195], v[116:119]
	v_mfma_i32_16x16x64_i8 v[112:115], v[154:157], v[192:195], v[112:115]
	v_mfma_i32_16x16x64_i8 v[104:107], v[146:149], v[200:203], v[104:107]
	v_mfma_i32_16x16x64_i8 v[96:99], v[154:157], v[200:203], v[96:99]
	v_mfma_i32_16x16x64_i8 v[88:91], v[146:149], v[208:211], v[88:91]
	v_mfma_i32_16x16x64_i8 v[80:83], v[154:157], v[208:211], v[80:83]
	v_mfma_i32_16x16x64_i8 v[108:111], v[158:161], v[174:177], v[108:111]
	v_mfma_i32_16x16x64_i8 v[100:103], v[166:169], v[174:177], v[100:103]
	v_mfma_i32_16x16x64_i8 v[92:95], v[158:161], v[188:191], v[92:95]
	v_mfma_i32_16x16x64_i8 v[84:87], v[166:169], v[188:191], v[84:87]
	v_mfma_i32_16x16x64_i8 v[76:79], v[158:161], v[196:199], v[76:79]
	v_mfma_i32_16x16x64_i8 v[72:75], v[166:169], v[196:199], v[72:75]
	v_mfma_i32_16x16x64_i8 v[68:71], v[158:161], v[204:207], v[68:71]
	v_mfma_i32_16x16x64_i8 v[64:67], v[166:169], v[204:207], v[64:67]
	v_mfma_i32_16x16x64_i8 v[108:111], v[162:165], v[184:187], v[108:111]
	v_mfma_i32_16x16x64_i8 v[100:103], v[170:173], v[184:187], v[100:103]
	v_mfma_i32_16x16x64_i8 v[92:95], v[162:165], v[192:195], v[92:95]
	v_mfma_i32_16x16x64_i8 v[84:87], v[170:173], v[192:195], v[84:87]
	v_mfma_i32_16x16x64_i8 v[76:79], v[162:165], v[200:203], v[76:79]
	v_mfma_i32_16x16x64_i8 v[72:75], v[170:173], v[200:203], v[72:75]
	v_mfma_i32_16x16x64_i8 v[68:71], v[162:165], v[208:211], v[68:71]
	v_mfma_i32_16x16x64_i8 v[64:67], v[170:173], v[208:211], v[64:67]
	s_setprio 0
	s_barrier
	s_add_i32 s24, s73, s93
	s_add_i32 m0, s24, 0xffffff80
	ds_read_b128 v[174:177], v183 offset:49152
	ds_read_b128 v[184:187], v183 offset:50176
	ds_read_b128 v[188:191], v183 offset:51200
	ds_read_b128 v[192:195], v183 offset:52224
	ds_read_b128 v[196:199], v183 offset:53248
	ds_read_b128 v[200:203], v183 offset:54272
	ds_read_b128 v[204:207], v183 offset:55296
	ds_read_b128 v[208:211], v183 offset:56320
	global_load_lds_dwordx4 v130, s[62:63] offset:128
	s_add_i32 m0, s24, 0x2000
	s_add_u32 s24, s62, 0x80080
	v_lshl_add_u64 v[178:179], v[212:213], 0, s[38:39]
	s_addc_u32 s25, s63, 0
	s_add_i32 s62, s66, s93
	global_load_lds_dwordx4 v[178:179], off
	s_mov_b32 m0, s62
	s_nop 0
	global_load_lds_dwordx4 v130, s[24:25]
	s_add_i32 m0, s62, 0x2000
	s_nop 0
	global_load_lds_dwordx4 v134, s[24:25]
	s_add_i32 m0, s77, 0xffffff80
	s_nop 0
	global_load_lds_dwordx4 v128, s[64:65] offset:128
	s_add_i32 m0, s78, 0xffffff80
	s_nop 0
	global_load_lds_dwordx4 v132, s[64:65] offset:128
	s_waitcnt vmcnt(8)
	s_waitcnt lgkmcnt(0)
	s_barrier
	s_setprio 1
	s_waitcnt lgkmcnt(0)
	v_mfma_i32_16x16x64_i8 v[60:63], v[142:145], v[174:177], v[60:63]
	v_mfma_i32_16x16x64_i8 v[56:59], v[150:153], v[174:177], v[56:59]
	v_mfma_i32_16x16x64_i8 v[52:55], v[142:145], v[188:191], v[52:55]
	v_mfma_i32_16x16x64_i8 v[48:51], v[150:153], v[188:191], v[48:51]
	v_mfma_i32_16x16x64_i8 v[44:47], v[142:145], v[196:199], v[44:47]
	v_mfma_i32_16x16x64_i8 v[40:43], v[150:153], v[196:199], v[40:43]
	v_mfma_i32_16x16x64_i8 v[36:39], v[142:145], v[204:207], v[36:39]
	v_mfma_i32_16x16x64_i8 v[32:35], v[150:153], v[204:207], v[32:35]
	v_mfma_i32_16x16x64_i8 v[60:63], v[146:149], v[184:187], v[60:63]
	v_mfma_i32_16x16x64_i8 v[56:59], v[154:157], v[184:187], v[56:59]
	v_mfma_i32_16x16x64_i8 v[52:55], v[146:149], v[192:195], v[52:55]
	v_mfma_i32_16x16x64_i8 v[48:51], v[154:157], v[192:195], v[48:51]
	v_mfma_i32_16x16x64_i8 v[44:47], v[146:149], v[200:203], v[44:47]
	v_mfma_i32_16x16x64_i8 v[40:43], v[154:157], v[200:203], v[40:43]
	v_mfma_i32_16x16x64_i8 v[36:39], v[146:149], v[208:211], v[36:39]
	v_mfma_i32_16x16x64_i8 v[32:35], v[154:157], v[208:211], v[32:35]
	v_mfma_i32_16x16x64_i8 v[28:31], v[158:161], v[174:177], v[28:31]
	v_mfma_i32_16x16x64_i8 v[24:27], v[166:169], v[174:177], v[24:27]
	v_mfma_i32_16x16x64_i8 v[20:23], v[158:161], v[188:191], v[20:23]
	v_mfma_i32_16x16x64_i8 v[16:19], v[166:169], v[188:191], v[16:19]
	v_mfma_i32_16x16x64_i8 v[12:15], v[158:161], v[196:199], v[12:15]
	v_mfma_i32_16x16x64_i8 v[8:11], v[166:169], v[196:199], v[8:11]
	v_mfma_i32_16x16x64_i8 v[4:7], v[158:161], v[204:207], v[4:7]
	v_mfma_i32_16x16x64_i8 v[0:3], v[166:169], v[204:207], v[0:3]
	v_mfma_i32_16x16x64_i8 v[28:31], v[162:165], v[184:187], v[28:31]
	v_mfma_i32_16x16x64_i8 v[24:27], v[170:173], v[184:187], v[24:27]
	v_mfma_i32_16x16x64_i8 v[20:23], v[162:165], v[192:195], v[20:23]
	v_mfma_i32_16x16x64_i8 v[16:19], v[170:173], v[192:195], v[16:19]
	v_mfma_i32_16x16x64_i8 v[12:15], v[162:165], v[200:203], v[12:15]
	v_mfma_i32_16x16x64_i8 v[8:11], v[170:173], v[200:203], v[8:11]
	v_mfma_i32_16x16x64_i8 v[4:7], v[162:165], v[208:211], v[4:7]
	v_mfma_i32_16x16x64_i8 v[0:3], v[170:173], v[208:211], v[0:3]
	s_setprio 0
	s_barrier
	s_add_u32 s60, s60, 0x100
	s_addc_u32 s61, s61, 0
	s_add_u32 vcc_lo, vcc_lo, 0x100
	s_addc_u32 vcc_hi, vcc_hi, 0
	s_cmp_ge_i32 s72, s91
	s_mov_b32 s62, s72
	s_cbranch_scc0 .LBB0_1297
	s_andn2_b64 vcc, exec, s[58:59]
	s_cbranch_vccnz .LBB0_1311
	global_load_dword v142, v131, s[10:11] sc1
	s_waitcnt vmcnt(0)
	v_cmp_lt_u32_e32 vcc, s7, v142
	s_cbranch_vccnz .LBB0_1310
	s_mov_b32 s41, 0x3ffff8
	s_branch .LBB0_1302

.LBB0_1444:
	ds_read_b128 v[24:27], v191
	ds_read_b128 v[28:31], v191 offset:1024
	ds_read_b128 v[16:19], v191 offset:2048
	ds_read_b128 v[20:23], v191 offset:3072
	ds_read_b128 v[8:11], v192
	ds_read_b128 v[12:15], v192 offset:1024
	s_waitcnt lgkmcnt(0)
	ds_read_b128 v[0:3], v192 offset:2048
	ds_read_b128 v[4:7], v192 offset:3072
	s_add_i32 vcc_hi, s62, 2
	s_add_u32 s60, s58, 0x100
	s_addc_u32 s61, s59, 0
	s_cmp_eq_u32 s53, s62
	s_cselect_b32 s62, s56, s97
	s_cselect_b32 s65, s55, s61
	s_cselect_b32 s64, s54, s60
	s_cselect_b32 s63, s57, vcc_lo
	s_add_i32 m0, s31, 0xc000
	ds_read_b128 v[172:175], v193
	ds_read_b128 v[176:179], v193 offset:1024
	ds_read_b128 v[194:197], v193 offset:2048
	ds_read_b128 v[198:201], v193 offset:3072
	ds_read_b128 v[202:205], v193 offset:4096
	ds_read_b128 v[206:209], v193 offset:5120
	ds_read_b128 v[210:213], v193 offset:6144
	ds_read_b128 v[214:217], v193 offset:7168
	global_load_lds_dwordx4 v166, s[58:59]
	s_add_i32 m0, s31, 0xe000
	s_nop 0
	global_load_lds_dwordx4 v168, s[58:59]
	s_waitcnt vmcnt(8)
	s_waitcnt lgkmcnt(0)
	s_barrier
	s_setprio 1
	s_waitcnt lgkmcnt(0)
	v_mfma_f32_16x16x128_f8f6f4 v[156:159], v[24:31], v[172:179], v[156:159]
	v_mfma_f32_16x16x128_f8f6f4 v[152:155], v[16:23], v[172:179], v[152:155]
	v_mfma_f32_16x16x128_f8f6f4 v[148:151], v[24:31], v[194:201], v[148:151]
	v_mfma_f32_16x16x128_f8f6f4 v[140:143], v[16:23], v[194:201], v[140:143]
	v_mfma_f32_16x16x128_f8f6f4 v[132:135], v[24:31], v[202:209], v[132:135]
	v_mfma_f32_16x16x128_f8f6f4 v[124:127], v[16:23], v[202:209], v[124:127]
	v_mfma_f32_16x16x128_f8f6f4 v[116:119], v[24:31], v[210:217], v[116:119]
	v_mfma_f32_16x16x128_f8f6f4 v[108:111], v[16:23], v[210:217], v[108:111]
	v_mfma_f32_16x16x128_f8f6f4 v[144:147], v[8:15], v[172:179], v[144:147]
	v_mfma_f32_16x16x128_f8f6f4 v[136:139], v[0:7], v[172:179], v[136:139]
	v_mfma_f32_16x16x128_f8f6f4 v[128:131], v[8:15], v[194:201], v[128:131]
	v_mfma_f32_16x16x128_f8f6f4 v[120:123], v[0:7], v[194:201], v[120:123]
	v_mfma_f32_16x16x128_f8f6f4 v[112:115], v[8:15], v[202:209], v[112:115]
	v_mfma_f32_16x16x128_f8f6f4 v[104:107], v[0:7], v[202:209], v[104:107]
	v_mfma_f32_16x16x128_f8f6f4 v[100:103], v[8:15], v[210:217], v[100:103]
	v_mfma_f32_16x16x128_f8f6f4 v[96:99], v[0:7], v[210:217], v[96:99]
	s_setprio 0
	s_barrier
	s_add_i32 s24, s82, s93
	s_mov_b32 m0, s24
	ds_read_b128 v[194:197], v193 offset:16384
	ds_read_b128 v[198:201], v193 offset:17408
	ds_read_b128 v[202:205], v193 offset:18432
	ds_read_b128 v[206:209], v193 offset:19456
	ds_read_b128 v[210:213], v193 offset:20480
	ds_read_b128 v[214:217], v193 offset:21504
	ds_read_b128 v[218:221], v193 offset:22528
	ds_read_b128 v[222:225], v193 offset:23552
	global_load_lds_dwordx4 v160, s[62:63]
	s_add_i32 m0, s24, 0x2000
	s_add_u32 s24, s62, 0x158000
	s_addc_u32 s25, s63, 0
	s_add_i32 s58, s83, s93
	global_load_lds_dwordx4 v162, s[62:63]
	s_mov_b32 m0, s58
	s_nop 0
	global_load_lds_dwordx4 v160, s[24:25]
	s_add_i32 m0, s58, 0x2000
	s_nop 0
	global_load_lds_dwordx4 v162, s[24:25]
	s_mov_b32 m0, s31
	s_nop 0
	global_load_lds_dwordx4 v160, s[64:65]
	s_mov_b32 m0, s47
	s_nop 0
	global_load_lds_dwordx4 v162, s[64:65]
	s_waitcnt vmcnt(8)
	s_waitcnt lgkmcnt(0)
	s_barrier
	s_setprio 1
	s_waitcnt lgkmcnt(0)
	v_mfma_f32_16x16x128_f8f6f4 v[92:95], v[24:31], v[194:201], v[92:95]
	v_mfma_f32_16x16x128_f8f6f4 v[88:91], v[16:23], v[194:201], v[88:91]
	v_mfma_f32_16x16x128_f8f6f4 v[84:87], v[24:31], v[202:209], v[84:87]
	v_mfma_f32_16x16x128_f8f6f4 v[72:75], v[16:23], v[202:209], v[72:75]
	v_mfma_f32_16x16x128_f8f6f4 v[68:71], v[24:31], v[210:217], v[68:71]
	v_mfma_f32_16x16x128_f8f6f4 v[56:59], v[16:23], v[210:217], v[56:59]
	v_mfma_f32_16x16x128_f8f6f4 v[52:55], v[24:31], v[218:225], v[52:55]
	v_mfma_f32_16x16x128_f8f6f4 v[40:43], v[16:23], v[218:225], v[40:43]
	v_mfma_f32_16x16x128_f8f6f4 v[80:83], v[8:15], v[194:201], v[80:83]
	v_mfma_f32_16x16x128_f8f6f4 v[76:79], v[0:7], v[194:201], v[76:79]
	v_mfma_f32_16x16x128_f8f6f4 v[64:67], v[8:15], v[202:209], v[64:67]
	v_mfma_f32_16x16x128_f8f6f4 v[60:63], v[0:7], v[202:209], v[60:63]
	v_mfma_f32_16x16x128_f8f6f4 v[48:51], v[8:15], v[210:217], v[48:51]
	v_mfma_f32_16x16x128_f8f6f4 v[44:47], v[0:7], v[210:217], v[44:47]
	v_mfma_f32_16x16x128_f8f6f4 v[36:39], v[8:15], v[218:225], v[36:39]
	v_mfma_f32_16x16x128_f8f6f4 v[32:35], v[0:7], v[218:225], v[32:35]
	s_setprio 0
	s_barrier
	s_add_i32 s58, 0, 0x18000
	s_add_i32 s59, 0, 0x1c000
	v_add_u32_e32 v12, s58, v187
	v_add_u32_e32 v28, s59, v187
	ds_read_b128 v[0:3], v12
	ds_read_b128 v[4:7], v12 offset:1024
	ds_read_b128 v[8:11], v12 offset:2048
	ds_read_b128 v[12:15], v12 offset:3072
	ds_read_b128 v[16:19], v28
	ds_read_b128 v[20:23], v28 offset:1024
	ds_read_b128 v[24:27], v28 offset:2048
	ds_read_b128 v[28:31], v28 offset:3072
	s_add_u32 s24, s64, 0x158000
	s_addc_u32 s25, s65, 0
	s_mov_b32 m0, s49
	ds_read_b128 v[194:197], v193 offset:32768
	ds_read_b128 v[198:201], v193 offset:33792
	ds_read_b128 v[202:205], v193 offset:34816
	ds_read_b128 v[206:209], v193 offset:35840
	ds_read_b128 v[210:213], v193 offset:36864
	ds_read_b128 v[214:217], v193 offset:37888
	ds_read_b128 v[218:221], v193 offset:38912
	ds_read_b128 v[222:225], v193 offset:39936
	global_load_lds_dwordx4 v160, s[24:25]
	s_mov_b32 m0, s69
	s_nop 0
	global_load_lds_dwordx4 v162, s[24:25]
	s_waitcnt vmcnt(8)
	s_waitcnt lgkmcnt(0)
	s_barrier
	s_setprio 1
	s_waitcnt lgkmcnt(0)
	v_mfma_f32_16x16x128_f8f6f4 v[156:159], v[0:7], v[194:201], v[156:159]
	v_mfma_f32_16x16x128_f8f6f4 v[152:155], v[8:15], v[194:201], v[152:155]
	v_mfma_f32_16x16x128_f8f6f4 v[148:151], v[0:7], v[202:209], v[148:151]
	v_mfma_f32_16x16x128_f8f6f4 v[140:143], v[8:15], v[202:209], v[140:143]
	v_mfma_f32_16x16x128_f8f6f4 v[132:135], v[0:7], v[210:217], v[132:135]
	v_mfma_f32_16x16x128_f8f6f4 v[124:127], v[8:15], v[210:217], v[124:127]
	v_mfma_f32_16x16x128_f8f6f4 v[116:119], v[0:7], v[218:225], v[116:119]
	v_mfma_f32_16x16x128_f8f6f4 v[108:111], v[8:15], v[218:225], v[108:111]
	v_mfma_f32_16x16x128_f8f6f4 v[144:147], v[16:23], v[194:201], v[144:147]
	v_mfma_f32_16x16x128_f8f6f4 v[136:139], v[24:31], v[194:201], v[136:139]
	v_mfma_f32_16x16x128_f8f6f4 v[128:131], v[16:23], v[202:209], v[128:131]
	v_mfma_f32_16x16x128_f8f6f4 v[120:123], v[24:31], v[202:209], v[120:123]
	v_mfma_f32_16x16x128_f8f6f4 v[112:115], v[16:23], v[210:217], v[112:115]
	v_mfma_f32_16x16x128_f8f6f4 v[104:107], v[24:31], v[210:217], v[104:107]
	v_mfma_f32_16x16x128_f8f6f4 v[100:103], v[16:23], v[218:225], v[100:103]
	v_mfma_f32_16x16x128_f8f6f4 v[96:99], v[24:31], v[218:225], v[96:99]
	s_setprio 0
	s_barrier
	s_add_i32 s24, s58, s93
	s_add_i32 m0, s24, 0xffffff80
	ds_read_b128 v[194:197], v193 offset:49152
	ds_read_b128 v[198:201], v193 offset:50176
	ds_read_b128 v[202:205], v193 offset:51200
	ds_read_b128 v[206:209], v193 offset:52224
	ds_read_b128 v[210:213], v193 offset:53248
	ds_read_b128 v[214:217], v193 offset:54272
	ds_read_b128 v[218:221], v193 offset:55296
	ds_read_b128 v[222:225], v193 offset:56320
	global_load_lds_dwordx4 v160, s[62:63] offset:128
	s_add_i32 m0, s24, 0x1f80
	s_add_u32 s24, s62, 0x158080
	s_addc_u32 s25, s63, 0
	s_add_i32 s58, s59, s93
	global_load_lds_dwordx4 v162, s[62:63] offset:128
	s_mov_b32 m0, s58
	s_nop 0
	global_load_lds_dwordx4 v160, s[24:25]
	s_add_i32 m0, s58, 0x2000
	s_nop 0
	global_load_lds_dwordx4 v162, s[24:25]
	s_add_i32 m0, s79, 0xffffff80
	s_nop 0
	global_load_lds_dwordx4 v160, s[64:65] offset:128
	s_add_i32 m0, s80, 0xffffff80
	s_nop 0
	global_load_lds_dwordx4 v162, s[64:65] offset:128
	s_waitcnt vmcnt(8)
	s_waitcnt lgkmcnt(0)
	s_barrier
	s_setprio 1
	s_waitcnt lgkmcnt(0)
	v_mfma_f32_16x16x128_f8f6f4 v[92:95], v[0:7], v[194:201], v[92:95]
	v_mfma_f32_16x16x128_f8f6f4 v[88:91], v[8:15], v[194:201], v[88:91]
	v_mfma_f32_16x16x128_f8f6f4 v[84:87], v[0:7], v[202:209], v[84:87]
	v_mfma_f32_16x16x128_f8f6f4 v[72:75], v[8:15], v[202:209], v[72:75]
	v_mfma_f32_16x16x128_f8f6f4 v[68:71], v[0:7], v[210:217], v[68:71]
	v_mfma_f32_16x16x128_f8f6f4 v[56:59], v[8:15], v[210:217], v[56:59]
	v_mfma_f32_16x16x128_f8f6f4 v[52:55], v[0:7], v[218:225], v[52:55]
	v_mfma_f32_16x16x128_f8f6f4 v[40:43], v[8:15], v[218:225], v[40:43]
	v_mfma_f32_16x16x128_f8f6f4 v[80:83], v[16:23], v[194:201], v[80:83]
	v_mfma_f32_16x16x128_f8f6f4 v[76:79], v[24:31], v[194:201], v[76:79]
	v_mfma_f32_16x16x128_f8f6f4 v[64:67], v[16:23], v[202:209], v[64:67]
	v_mfma_f32_16x16x128_f8f6f4 v[60:63], v[24:31], v[202:209], v[60:63]
	v_mfma_f32_16x16x128_f8f6f4 v[48:51], v[16:23], v[210:217], v[48:51]
	v_mfma_f32_16x16x128_f8f6f4 v[44:47], v[24:31], v[210:217], v[44:47]
	v_mfma_f32_16x16x128_f8f6f4 v[36:39], v[16:23], v[218:225], v[36:39]
	v_mfma_f32_16x16x128_f8f6f4 v[32:35], v[24:31], v[218:225], v[32:35]
	s_setprio 0
	s_barrier
	s_add_u32 s97, s97, 0x100
	s_addc_u32 vcc_lo, vcc_lo, 0
	s_cmp_ge_i32 vcc_hi, s96
	s_mov_b64 s[58:59], s[60:61]
	s_mov_b32 s62, vcc_hi
	s_cbranch_scc0 .LBB0_1444
	s_nop 15
	s_nop 15
	s_and_b64 vcc, exec, s[94:95]
	s_cbranch_vccz .LBB0_1447
	s_barrier

.LBB0_1588:
	ds_read_b128 v[24:27], v218
	ds_read_b128 v[28:31], v218 offset:1024
	ds_read_b128 v[16:19], v218 offset:2048
	ds_read_b128 v[20:23], v218 offset:3072
	ds_read_b128 v[8:11], v219
	ds_read_b128 v[12:15], v219 offset:1024
	ds_read_b128 v[0:3], v219 offset:2048
	ds_read_b128 v[4:7], v219 offset:3072
	s_add_i32 s79, s52, 2
	s_add_u32 s53, s50, 0xfff80080
	s_addc_u32 s54, s51, -1
	s_cmp_eq_u32 s76, s52
	s_cselect_b32 s52, s75, s77
	s_cselect_b32 s55, s31, s54
	s_cselect_b32 s54, s37, s53
	s_cselect_b32 s53, s35, s78
	s_add_i32 m0, s47, 0xc000
	ds_read_b128 v[160:163], v220
	ds_read_b128 v[164:167], v220 offset:1024
	ds_read_b128 v[168:171], v220 offset:2048
	ds_read_b128 v[172:175], v220 offset:3072
	ds_read_b128 v[176:179], v220 offset:4096
	ds_read_b128 v[180:183], v220 offset:5120
	ds_read_b128 v[184:187], v220 offset:6144
	ds_read_b128 v[188:191], v220 offset:7168
	global_load_lds_dwordx4 v196, s[50:51]
	s_add_i32 m0, s47, 0xe000
	s_nop 0
	global_load_lds_dwordx4 v198, s[50:51]
	s_waitcnt vmcnt(8)
	s_waitcnt lgkmcnt(0)
	s_barrier
	s_setprio 1
	s_waitcnt lgkmcnt(0)
	v_mfma_f32_16x16x128_f8f6f4 v[156:159], v[24:31], v[160:167], v[156:159]
	v_mfma_f32_16x16x128_f8f6f4 v[152:155], v[16:23], v[160:167], v[152:155]
	v_mfma_f32_16x16x128_f8f6f4 v[148:151], v[24:31], v[168:175], v[148:151]
	v_mfma_f32_16x16x128_f8f6f4 v[140:143], v[16:23], v[168:175], v[140:143]
	v_mfma_f32_16x16x128_f8f6f4 v[132:135], v[24:31], v[176:183], v[132:135]
	v_mfma_f32_16x16x128_f8f6f4 v[124:127], v[16:23], v[176:183], v[124:127]
	v_mfma_f32_16x16x128_f8f6f4 v[116:119], v[24:31], v[184:191], v[116:119]
	v_mfma_f32_16x16x128_f8f6f4 v[108:111], v[16:23], v[184:191], v[108:111]
	v_mfma_f32_16x16x128_f8f6f4 v[144:147], v[8:15], v[160:167], v[144:147]
	v_mfma_f32_16x16x128_f8f6f4 v[136:139], v[0:7], v[160:167], v[136:139]
	v_mfma_f32_16x16x128_f8f6f4 v[128:131], v[8:15], v[168:175], v[128:131]
	v_mfma_f32_16x16x128_f8f6f4 v[120:123], v[0:7], v[168:175], v[120:123]
	v_mfma_f32_16x16x128_f8f6f4 v[112:115], v[8:15], v[176:183], v[112:115]
	v_mfma_f32_16x16x128_f8f6f4 v[104:107], v[0:7], v[176:183], v[104:107]
	v_mfma_f32_16x16x128_f8f6f4 v[100:103], v[8:15], v[184:191], v[100:103]
	v_mfma_f32_16x16x128_f8f6f4 v[96:99], v[0:7], v[184:191], v[96:99]
	s_setprio 0
	s_barrier
	s_add_i32 s80, s66, s93
	s_mov_b32 m0, s80
	ds_read_b128 v[168:171], v220 offset:16384
	ds_read_b128 v[172:175], v220 offset:17408
	ds_read_b128 v[176:179], v220 offset:18432
	ds_read_b128 v[180:183], v220 offset:19456
	ds_read_b128 v[184:187], v220 offset:20480
	ds_read_b128 v[188:191], v220 offset:21504
	ds_read_b128 v[202:205], v220 offset:22528
	ds_read_b128 v[206:209], v220 offset:23552
	global_load_lds_dwordx4 v192, s[52:53]
	s_add_i32 m0, s80, 0x2000
	s_add_u32 s80, s52, 0x80000
	v_lshl_add_u64 v[162:163], s[52:53], 0, v[194:195]
	s_addc_u32 s81, s53, 0
	s_add_i32 s82, s68, s93
	global_load_lds_dwordx4 v194, s[52:53]
	s_mov_b32 m0, s82
	v_lshl_add_u64 v[166:167], s[54:55], 0, v[194:195]
	global_load_lds_dwordx4 v192, s[80:81]
	s_add_i32 m0, s82, 0x2000
	s_nop 0
	global_load_lds_dwordx4 v194, s[80:81]
	v_lshl_add_u64 v[164:165], s[54:55], 0, v[192:193]
	s_mov_b32 m0, s47
	s_nop 0
	global_load_lds_dwordx4 v192, s[54:55]
	s_mov_b32 m0, s58
	s_nop 0
	global_load_lds_dwordx4 v194, s[54:55]
	s_waitcnt vmcnt(8)
	s_waitcnt lgkmcnt(0)
	s_barrier
	s_setprio 1
	s_waitcnt lgkmcnt(0)
	v_mfma_f32_16x16x128_f8f6f4 v[92:95], v[24:31], v[168:175], v[92:95]
	v_mfma_f32_16x16x128_f8f6f4 v[88:91], v[16:23], v[168:175], v[88:91]
	v_mfma_f32_16x16x128_f8f6f4 v[84:87], v[24:31], v[176:183], v[84:87]
	v_mfma_f32_16x16x128_f8f6f4 v[72:75], v[16:23], v[176:183], v[72:75]
	v_mfma_f32_16x16x128_f8f6f4 v[68:71], v[24:31], v[184:191], v[68:71]
	v_mfma_f32_16x16x128_f8f6f4 v[56:59], v[16:23], v[184:191], v[56:59]
	v_mfma_f32_16x16x128_f8f6f4 v[52:55], v[24:31], v[202:209], v[52:55]
	v_mfma_f32_16x16x128_f8f6f4 v[44:47], v[16:23], v[202:209], v[44:47]
	v_mfma_f32_16x16x128_f8f6f4 v[80:83], v[8:15], v[168:175], v[80:83]
	v_mfma_f32_16x16x128_f8f6f4 v[76:79], v[0:7], v[168:175], v[76:79]
	v_mfma_f32_16x16x128_f8f6f4 v[64:67], v[8:15], v[176:183], v[64:67]
	v_mfma_f32_16x16x128_f8f6f4 v[60:63], v[0:7], v[176:183], v[60:63]
	v_mfma_f32_16x16x128_f8f6f4 v[48:51], v[8:15], v[184:191], v[48:51]
	v_mfma_f32_16x16x128_f8f6f4 v[40:43], v[0:7], v[184:191], v[40:43]
	v_mfma_f32_16x16x128_f8f6f4 v[36:39], v[8:15], v[202:209], v[36:39]
	v_mfma_f32_16x16x128_f8f6f4 v[32:35], v[0:7], v[202:209], v[32:35]
	s_setprio 0
	s_barrier
	s_add_i32 s80, 0, 0x18000
	s_add_i32 s81, 0, 0x1c000
	v_add_u32_e32 v12, s80, v215
	v_add_u32_e32 v28, s81, v215
	ds_read_b128 v[0:3], v12
	ds_read_b128 v[4:7], v12 offset:1024
	ds_read_b128 v[8:11], v12 offset:2048
	ds_read_b128 v[12:15], v12 offset:3072
	ds_read_b128 v[16:19], v28
	ds_read_b128 v[20:23], v28 offset:1024
	ds_read_b128 v[24:27], v28 offset:2048
	ds_read_b128 v[28:31], v28 offset:3072
	s_add_u32 s54, s54, 0x80000
	s_addc_u32 s55, s55, 0
	s_mov_b32 m0, s59
	ds_read_b128 v[168:171], v220 offset:32768
	ds_read_b128 v[172:175], v220 offset:33792
	ds_read_b128 v[176:179], v220 offset:34816
	ds_read_b128 v[180:183], v220 offset:35840
	ds_read_b128 v[184:187], v220 offset:36864
	ds_read_b128 v[188:191], v220 offset:37888
	ds_read_b128 v[202:205], v220 offset:38912
	ds_read_b128 v[206:209], v220 offset:39936
	global_load_lds_dwordx4 v192, s[54:55]
	s_mov_b32 m0, s60
	s_nop 0
	global_load_lds_dwordx4 v194, s[54:55]
	s_waitcnt vmcnt(8)
	s_waitcnt lgkmcnt(0)
	s_barrier
	s_setprio 1
	s_waitcnt lgkmcnt(0)
	v_mfma_f32_16x16x128_f8f6f4 v[156:159], v[0:7], v[168:175], v[156:159]
	v_mfma_f32_16x16x128_f8f6f4 v[152:155], v[8:15], v[168:175], v[152:155]
	v_mfma_f32_16x16x128_f8f6f4 v[148:151], v[0:7], v[176:183], v[148:151]
	v_mfma_f32_16x16x128_f8f6f4 v[140:143], v[8:15], v[176:183], v[140:143]
	v_mfma_f32_16x16x128_f8f6f4 v[132:135], v[0:7], v[184:191], v[132:135]
	v_mfma_f32_16x16x128_f8f6f4 v[124:127], v[8:15], v[184:191], v[124:127]
	v_mfma_f32_16x16x128_f8f6f4 v[116:119], v[0:7], v[202:209], v[116:119]
	v_mfma_f32_16x16x128_f8f6f4 v[108:111], v[8:15], v[202:209], v[108:111]
	v_mfma_f32_16x16x128_f8f6f4 v[144:147], v[16:23], v[168:175], v[144:147]
	v_mfma_f32_16x16x128_f8f6f4 v[136:139], v[24:31], v[168:175], v[136:139]
	v_mfma_f32_16x16x128_f8f6f4 v[128:131], v[16:23], v[176:183], v[128:131]
	v_mfma_f32_16x16x128_f8f6f4 v[120:123], v[24:31], v[176:183], v[120:123]
	v_mfma_f32_16x16x128_f8f6f4 v[112:115], v[16:23], v[184:191], v[112:115]
	v_mfma_f32_16x16x128_f8f6f4 v[104:107], v[24:31], v[184:191], v[104:107]
	v_mfma_f32_16x16x128_f8f6f4 v[100:103], v[16:23], v[202:209], v[100:103]
	v_mfma_f32_16x16x128_f8f6f4 v[96:99], v[24:31], v[202:209], v[96:99]
	s_setprio 0
	s_barrier
	s_add_i32 s54, s80, s93
	s_add_i32 m0, s54, 0xffffff80
	ds_read_b128 v[168:171], v220 offset:49152
	ds_read_b128 v[172:175], v220 offset:50176
	ds_read_b128 v[176:179], v220 offset:51200
	ds_read_b128 v[180:183], v220 offset:52224
	ds_read_b128 v[184:187], v220 offset:53248
	ds_read_b128 v[188:191], v220 offset:54272
	ds_read_b128 v[202:205], v220 offset:55296
	ds_read_b128 v[206:209], v220 offset:56320
	global_load_lds_dwordx4 v192, s[52:53] offset:128
	s_add_i32 m0, s54, 0x2000
	s_add_u32 s52, s52, 0x80080
	v_lshl_add_u64 v[160:161], v[162:163], 0, s[24:25]
	s_addc_u32 s53, s53, 0
	s_add_i32 s54, s81, s93
	global_load_lds_dwordx4 v[160:161], off
	s_mov_b32 m0, s54
	s_nop 0
	global_load_lds_dwordx4 v192, s[52:53]
	s_add_i32 m0, s54, 0x2000
	s_nop 0
	global_load_lds_dwordx4 v194, s[52:53]
	v_lshl_add_u64 v[160:161], v[164:165], 0, s[24:25]
	s_mov_b32 m0, s64
	s_nop 0
	global_load_lds_dwordx4 v[160:161], off
	v_lshl_add_u64 v[160:161], v[166:167], 0, s[24:25]
	s_mov_b32 m0, s65
	s_nop 0
	global_load_lds_dwordx4 v[160:161], off
	s_waitcnt vmcnt(8)
	s_waitcnt lgkmcnt(0)
	s_barrier
	s_setprio 1
	s_waitcnt lgkmcnt(0)
	v_mfma_f32_16x16x128_f8f6f4 v[92:95], v[0:7], v[168:175], v[92:95]
	v_mfma_f32_16x16x128_f8f6f4 v[88:91], v[8:15], v[168:175], v[88:91]
	v_mfma_f32_16x16x128_f8f6f4 v[84:87], v[0:7], v[176:183], v[84:87]
	v_mfma_f32_16x16x128_f8f6f4 v[72:75], v[8:15], v[176:183], v[72:75]
	v_mfma_f32_16x16x128_f8f6f4 v[68:71], v[0:7], v[184:191], v[68:71]
	v_mfma_f32_16x16x128_f8f6f4 v[56:59], v[8:15], v[184:191], v[56:59]
	v_mfma_f32_16x16x128_f8f6f4 v[52:55], v[0:7], v[202:209], v[52:55]
	v_mfma_f32_16x16x128_f8f6f4 v[44:47], v[8:15], v[202:209], v[44:47]
	v_mfma_f32_16x16x128_f8f6f4 v[80:83], v[16:23], v[168:175], v[80:83]
	v_mfma_f32_16x16x128_f8f6f4 v[76:79], v[24:31], v[168:175], v[76:79]
	v_mfma_f32_16x16x128_f8f6f4 v[64:67], v[16:23], v[176:183], v[64:67]
	v_mfma_f32_16x16x128_f8f6f4 v[60:63], v[24:31], v[176:183], v[60:63]
	v_mfma_f32_16x16x128_f8f6f4 v[48:51], v[16:23], v[184:191], v[48:51]
	v_mfma_f32_16x16x128_f8f6f4 v[40:43], v[24:31], v[184:191], v[40:43]
	v_mfma_f32_16x16x128_f8f6f4 v[36:39], v[16:23], v[202:209], v[36:39]
	v_mfma_f32_16x16x128_f8f6f4 v[32:35], v[24:31], v[202:209], v[32:35]
	s_setprio 0
	s_barrier
	s_add_u32 s50, s50, 0x100
	s_addc_u32 s51, s51, 0
	s_add_u32 s77, s77, 0x100
	s_addc_u32 s78, s78, 0
	s_cmp_ge_i32 s79, s45
	s_mov_b32 s52, s79
	s_cbranch_scc0 .LBB0_1588
	s_nop 15
	s_nop 15
	s_andn2_b64 vcc, exec, s[48:49]
	s_cbranch_vccnz .LBB0_1602
	global_load_dword v0, v193, s[6:7] sc1
	s_waitcnt vmcnt(0)
	v_cmp_le_u32_e32 vcc, s88, v0
	s_cbranch_vccnz .LBB0_1601
	s_mov_b32 s31, 0x3ffff8
	s_branch .LBB0_1593
